# K/Q epilogue: per-row sum of squares as one mul + 7 fmac chain instead of the pairwise tree (48 fewer VALU per K/Q tile per wave)
# baseline (speedup 1.0000x reference)
.LBB0_745:
	s_or_b64 exec, exec, s[64:65]
	v_ashrrev_i32_e32 v219, 31, v218
	v_lshl_add_u64 v[202:203], v[218:219], 2, s[10:11]
	global_load_dword v200, v[202:203], off sc1
	global_load_dword v249, v[202:203], off offset:64 sc1
	global_load_dword v248, v[202:203], off offset:128 sc1
	global_load_dword v247, v[202:203], off offset:192 sc1
	global_load_dword v246, v[202:203], off offset:512 sc1
	global_load_dword v245, v[202:203], off offset:576 sc1
	global_load_dword v241, v[202:203], off offset:640 sc1
	global_load_dword v219, v[202:203], off offset:704 sc1
	v_mul_f32_e32 v202, v125, v125
	v_fmac_f32_e32 v202, v127, v127
	v_fmac_f32_e32 v202, v124, v124
	v_fmac_f32_e32 v202, v126, v126
	v_fmac_f32_e32 v202, v121, v121
	v_fmac_f32_e32 v202, v120, v120
	v_fmac_f32_e32 v202, v123, v123
	v_fmac_f32_e32 v202, v122, v122
	v_mov_b32_e32 v203, v202
	s_nop 1
	v_permlane16_swap_b32_e32 v202, v203
	v_add_f32_e32 v203, v202, v203
	v_lshlrev_b32_e32 v250, 5, v240
	v_mov_b32_e32 v204, v203
	s_nop 1
	v_permlane32_swap_b32_e32 v203, v204
	v_add_u32_e32 v202, s79, v250
	s_and_saveexec_b64 s[60:61], s[8:9]
	v_add_f32_e32 v203, v203, v204
	ds_write_b32 v202, v203
	s_or_b64 exec, exec, s[60:61]
	v_mul_f32_e32 v203, v105, v105
	v_fmac_f32_e32 v203, v107, v107
	v_fmac_f32_e32 v203, v104, v104
	v_fmac_f32_e32 v203, v106, v106
	v_fmac_f32_e32 v203, v97, v97
	v_fmac_f32_e32 v203, v96, v96
	v_fmac_f32_e32 v203, v99, v99
	v_fmac_f32_e32 v203, v98, v98
	v_mov_b32_e32 v204, v203
	s_nop 1
	v_permlane16_swap_b32_e32 v203, v204
	v_add_f32_e32 v203, v203, v204
	v_mov_b32_e32 v204, v203
	s_nop 1
	v_permlane32_swap_b32_e32 v203, v204
	s_and_saveexec_b64 s[60:61], s[8:9]
	v_add_f32_e32 v203, v203, v204
	ds_write_b32 v202, v203 offset:16
	s_or_b64 exec, exec, s[60:61]
	v_mul_f32_e32 v203, v117, v117
	v_fmac_f32_e32 v203, v119, v119
	v_fmac_f32_e32 v203, v116, v116
	v_fmac_f32_e32 v203, v118, v118
	v_fmac_f32_e32 v203, v113, v113
	v_fmac_f32_e32 v203, v112, v112
	v_fmac_f32_e32 v203, v115, v115
	v_fmac_f32_e32 v203, v114, v114
	v_mov_b32_e32 v204, v203
	s_nop 1
	v_permlane16_swap_b32_e32 v203, v204
	v_add_f32_e32 v203, v203, v204
	v_mov_b32_e32 v204, v203
	s_nop 1
	v_permlane32_swap_b32_e32 v203, v204
	s_and_saveexec_b64 s[60:61], s[8:9]
	v_add_f32_e32 v203, v203, v204
	ds_write_b32 v202, v203 offset:512
	s_or_b64 exec, exec, s[60:61]
	v_mul_f32_e32 v203, v89, v89
	v_fmac_f32_e32 v203, v91, v91
	v_fmac_f32_e32 v203, v88, v88
	v_fmac_f32_e32 v203, v90, v90
	v_fmac_f32_e32 v203, v85, v85
	v_fmac_f32_e32 v203, v84, v84
	v_fmac_f32_e32 v203, v87, v87
	v_fmac_f32_e32 v203, v86, v86
	v_mov_b32_e32 v204, v203
	s_nop 1
	v_permlane16_swap_b32_e32 v203, v204
	v_add_f32_e32 v203, v203, v204
	v_mov_b32_e32 v204, v203
	s_nop 1
	v_permlane32_swap_b32_e32 v203, v204
	s_and_saveexec_b64 s[60:61], s[8:9]
	v_add_f32_e32 v203, v203, v204
	ds_write_b32 v202, v203 offset:528
	s_or_b64 exec, exec, s[60:61]
	v_mul_f32_e32 v203, v109, v109
	v_fmac_f32_e32 v203, v111, v111
	v_fmac_f32_e32 v203, v108, v108
	v_fmac_f32_e32 v203, v110, v110
	v_fmac_f32_e32 v203, v101, v101
	v_fmac_f32_e32 v203, v100, v100
	v_fmac_f32_e32 v203, v103, v103
	v_fmac_f32_e32 v203, v102, v102
	v_mov_b32_e32 v204, v203
	s_nop 1
	v_permlane16_swap_b32_e32 v203, v204
	v_add_f32_e32 v203, v203, v204
	v_mov_b32_e32 v204, v203
	s_nop 1
	v_permlane32_swap_b32_e32 v203, v204
	s_and_saveexec_b64 s[60:61], s[8:9]
	v_add_f32_e32 v203, v203, v204
	ds_write_b32 v202, v203 offset:1024
	s_or_b64 exec, exec, s[60:61]
	v_mul_f32_e32 v203, v77, v77
	v_fmac_f32_e32 v203, v79, v79
	v_fmac_f32_e32 v203, v76, v76
	v_fmac_f32_e32 v203, v78, v78
	v_fmac_f32_e32 v203, v73, v73
	v_fmac_f32_e32 v203, v72, v72
	v_fmac_f32_e32 v203, v75, v75
	v_fmac_f32_e32 v203, v74, v74
	v_mov_b32_e32 v204, v203
	s_nop 1
	v_permlane16_swap_b32_e32 v203, v204
	v_add_f32_e32 v203, v203, v204
	v_mov_b32_e32 v204, v203
	s_nop 1
	v_permlane32_swap_b32_e32 v203, v204
	s_and_saveexec_b64 s[60:61], s[8:9]
	v_add_f32_e32 v203, v203, v204
	ds_write_b32 v202, v203 offset:1040
	s_or_b64 exec, exec, s[60:61]
	v_mul_f32_e32 v203, v93, v93
	v_fmac_f32_e32 v203, v95, v95
	v_fmac_f32_e32 v203, v92, v92
	v_fmac_f32_e32 v203, v94, v94
	v_fmac_f32_e32 v203, v81, v81
	v_fmac_f32_e32 v203, v80, v80
	v_fmac_f32_e32 v203, v83, v83
	v_fmac_f32_e32 v203, v82, v82
	v_mov_b32_e32 v204, v203
	s_nop 1
	v_permlane16_swap_b32_e32 v203, v204
	v_add_f32_e32 v203, v203, v204
	v_mov_b32_e32 v204, v203
	s_nop 1
	v_permlane32_swap_b32_e32 v203, v204
	s_and_saveexec_b64 s[60:61], s[8:9]
	v_add_f32_e32 v203, v203, v204
	ds_write_b32 v202, v203 offset:1536
	s_or_b64 exec, exec, s[60:61]
	v_mul_f32_e32 v203, v69, v69
	v_fmac_f32_e32 v203, v71, v71
	v_fmac_f32_e32 v203, v68, v68
	v_fmac_f32_e32 v203, v70, v70
	v_fmac_f32_e32 v203, v65, v65
	v_fmac_f32_e32 v203, v64, v64
	v_fmac_f32_e32 v203, v67, v67
	v_fmac_f32_e32 v203, v66, v66
	v_mov_b32_e32 v204, v203
	s_nop 1
	v_permlane16_swap_b32_e32 v203, v204
	v_add_f32_e32 v203, v203, v204
	v_mov_b32_e32 v204, v203
	s_nop 1
	v_permlane32_swap_b32_e32 v203, v204
	s_and_saveexec_b64 s[60:61], s[8:9]
	v_add_f32_e32 v203, v203, v204
	ds_write_b32 v202, v203 offset:1552
	s_or_b64 exec, exec, s[60:61]
	v_mul_f32_e32 v203, v61, v61
	v_fmac_f32_e32 v203, v63, v63
	v_fmac_f32_e32 v203, v60, v60
	v_fmac_f32_e32 v203, v62, v62
	v_fmac_f32_e32 v203, v57, v57
	v_fmac_f32_e32 v203, v56, v56
	v_fmac_f32_e32 v203, v59, v59
	v_fmac_f32_e32 v203, v58, v58
	v_mov_b32_e32 v204, v203
	s_nop 1
	v_permlane16_swap_b32_e32 v203, v204
	v_add_f32_e32 v203, v203, v204
	v_mov_b32_e32 v204, v203
	s_nop 1
	v_permlane32_swap_b32_e32 v203, v204
	s_and_saveexec_b64 s[60:61], s[8:9]
	v_add_f32_e32 v203, v203, v204
	ds_write_b32 v202, v203 offset:4096
	s_or_b64 exec, exec, s[60:61]
	v_mul_f32_e32 v203, v53, v53
	v_fmac_f32_e32 v203, v55, v55
	v_fmac_f32_e32 v203, v52, v52
	v_fmac_f32_e32 v203, v54, v54
	v_fmac_f32_e32 v203, v45, v45
	v_fmac_f32_e32 v203, v44, v44
	v_fmac_f32_e32 v203, v47, v47
	v_fmac_f32_e32 v203, v46, v46
	v_mov_b32_e32 v204, v203
	s_nop 1
	v_permlane16_swap_b32_e32 v203, v204
	v_add_f32_e32 v203, v203, v204
	v_mov_b32_e32 v204, v203
	s_nop 1
	v_permlane32_swap_b32_e32 v203, v204
	s_and_saveexec_b64 s[60:61], s[8:9]
	v_add_f32_e32 v203, v203, v204
	ds_write_b32 v202, v203 offset:4112
	s_or_b64 exec, exec, s[60:61]
	v_mul_f32_e32 v203, v49, v49
	v_fmac_f32_e32 v203, v51, v51
	v_fmac_f32_e32 v203, v48, v48
	v_fmac_f32_e32 v203, v50, v50
	v_fmac_f32_e32 v203, v41, v41
	v_fmac_f32_e32 v203, v40, v40
	v_fmac_f32_e32 v203, v43, v43
	v_fmac_f32_e32 v203, v42, v42
	v_mov_b32_e32 v204, v203
	s_nop 1
	v_permlane16_swap_b32_e32 v203, v204
	v_add_f32_e32 v203, v203, v204
	v_mov_b32_e32 v204, v203
	s_nop 1
	v_permlane32_swap_b32_e32 v203, v204
	s_and_saveexec_b64 s[60:61], s[8:9]
	v_add_f32_e32 v203, v203, v204
	ds_write_b32 v202, v203 offset:4608
	s_or_b64 exec, exec, s[60:61]
	v_mul_f32_e32 v203, v37, v37
	v_fmac_f32_e32 v203, v39, v39
	v_fmac_f32_e32 v203, v36, v36
	v_fmac_f32_e32 v203, v38, v38
	v_fmac_f32_e32 v203, v29, v29
	v_fmac_f32_e32 v203, v28, v28
	v_fmac_f32_e32 v203, v31, v31
	v_fmac_f32_e32 v203, v30, v30
	v_mov_b32_e32 v204, v203
	s_nop 1
	v_permlane16_swap_b32_e32 v203, v204
	v_add_f32_e32 v203, v203, v204
	v_mov_b32_e32 v204, v203
	s_nop 1
	v_permlane32_swap_b32_e32 v203, v204
	s_and_saveexec_b64 s[60:61], s[8:9]
	v_add_f32_e32 v203, v203, v204
	ds_write_b32 v202, v203 offset:4624
	s_or_b64 exec, exec, s[60:61]
	v_mul_f32_e32 v203, v33, v33
	v_fmac_f32_e32 v203, v35, v35
	v_fmac_f32_e32 v203, v32, v32
	v_fmac_f32_e32 v203, v34, v34
	v_fmac_f32_e32 v203, v25, v25
	v_fmac_f32_e32 v203, v24, v24
	v_fmac_f32_e32 v203, v27, v27
	v_fmac_f32_e32 v203, v26, v26
	v_mov_b32_e32 v204, v203
	s_nop 1
	v_permlane16_swap_b32_e32 v203, v204
	v_add_f32_e32 v203, v203, v204
	v_mov_b32_e32 v204, v203
	s_nop 1
	v_permlane32_swap_b32_e32 v203, v204
	s_and_saveexec_b64 s[60:61], s[8:9]
	v_add_f32_e32 v203, v203, v204
	ds_write_b32 v202, v203 offset:5120
	s_or_b64 exec, exec, s[60:61]
	v_mul_f32_e32 v203, v21, v21
	v_fmac_f32_e32 v203, v23, v23
	v_fmac_f32_e32 v203, v20, v20
	v_fmac_f32_e32 v203, v22, v22
	v_fmac_f32_e32 v203, v13, v13
	v_fmac_f32_e32 v203, v12, v12
	v_fmac_f32_e32 v203, v15, v15
	v_fmac_f32_e32 v203, v14, v14
	v_mov_b32_e32 v204, v203
	s_nop 1
	v_permlane16_swap_b32_e32 v203, v204
	v_add_f32_e32 v203, v203, v204
	v_mov_b32_e32 v204, v203
	s_nop 1
	v_permlane32_swap_b32_e32 v203, v204
	s_and_saveexec_b64 s[60:61], s[8:9]
	v_add_f32_e32 v203, v203, v204
	ds_write_b32 v202, v203 offset:5136
	s_or_b64 exec, exec, s[60:61]
	v_mul_f32_e32 v203, v17, v17
	v_fmac_f32_e32 v203, v19, v19
	v_fmac_f32_e32 v203, v16, v16
	v_fmac_f32_e32 v203, v18, v18
	v_fmac_f32_e32 v203, v9, v9
	v_fmac_f32_e32 v203, v8, v8
	v_fmac_f32_e32 v203, v11, v11
	v_fmac_f32_e32 v203, v10, v10
	v_mov_b32_e32 v204, v203
	s_nop 1
	v_permlane16_swap_b32_e32 v203, v204
	v_add_f32_e32 v203, v203, v204
	v_mov_b32_e32 v204, v203
	s_nop 1
	v_permlane32_swap_b32_e32 v203, v204
	s_and_saveexec_b64 s[60:61], s[8:9]
	v_add_f32_e32 v203, v203, v204
	ds_write_b32 v202, v203 offset:5632
	s_or_b64 exec, exec, s[60:61]
	v_mul_f32_e32 v203, v5, v5
	v_fmac_f32_e32 v203, v7, v7
	v_fmac_f32_e32 v203, v4, v4
	v_fmac_f32_e32 v203, v6, v6
	v_fmac_f32_e32 v203, v1, v1
	v_fmac_f32_e32 v203, v0, v0
	v_fmac_f32_e32 v203, v3, v3
	v_fmac_f32_e32 v203, v2, v2
	v_mov_b32_e32 v204, v203
	s_nop 1
	v_permlane16_swap_b32_e32 v203, v204
	v_add_f32_e32 v203, v203, v204
	v_mov_b32_e32 v204, v203
	s_nop 1
	v_permlane32_swap_b32_e32 v203, v204
	s_and_saveexec_b64 s[60:61], s[8:9]
	v_add_f32_e32 v203, v203, v204
	ds_write_b32 v202, v203 offset:5648
	s_or_b64 exec, exec, s[60:61]
	s_and_b64 s[60:61], s[62:63], exec
	s_cselect_b32 s60, s92, 0xc00
	s_lshr_b32 s61, s50, 1
	s_add_i32 s50, s50, -6
	s_lshr_b32 s64, s50, 2
	s_and_b64 s[50:51], s[62:63], exec
	s_cselect_b32 s61, s61, s64
	s_add_i32 s64, s39, 0xfffffa00
	v_add_u32_e32 v202, s80, v239
	v_mov_b32_e32 v203, s78
	s_and_b64 s[50:51], s[62:63], exec
	v_cndmask_b32_e64 v222, v202, v203, s[8:9]
	v_or_b32_e32 v202, 4, v202
	v_mov_b32_e32 v203, s81
	v_cndmask_b32_e64 v220, v202, v203, s[8:9]
	s_cselect_b32 s8, 0, 0x600
	s_cselect_b32 s50, s39, s64
	s_add_u32 s51, s82, s8
	s_addc_u32 s64, s83, 0
	s_lshl_b32 s8, s61, 7
	s_ashr_i32 s9, s8, 31
	s_lshl_b64 s[8:9], s[8:9], 2
	s_add_u32 s8, s51, s8
	s_addc_u32 s9, s64, s9
	v_ashrrev_i32_e32 v223, 31, v222
	v_ashrrev_i32_e32 v221, 31, v220
	s_waitcnt lgkmcnt(0)
	s_barrier
	s_waitcnt vmcnt(0)
	v_fmamk_f32 v204, v200, 0x3a800000, v238
	v_add_u32_e32 v200, 0x20000, v250
	ds_read_b128 v[200:203], v200
	v_mul_f32_e32 v251, 0x358637bd, v204
	v_mov_b32_e32 v205, 0x3e0293ee
	v_cndmask_b32_e64 v244, v205, 1.0, s[62:63]
	v_mad_i64_i32 v[204:205], s[8:9], s60, v218, 0
	s_waitcnt lgkmcnt(0)
	v_pk_add_f32 v[200:201], v[200:201], v[202:203]
	s_ashr_i32 s51, s50, 31
	v_add_f32_e32 v200, v200, v201
	v_fmamk_f32 v200, v200, 0x3c000000, v251
	v_rsq_f32_e32 v200, v200
	s_lshl_b64 s[8:9], s[50:51], 1
	s_add_u32 s8, s48, s8
	s_addc_u32 s9, s49, s9
	v_mul_f32_e32 v200, v244, v200
	v_pk_mul_f32 v[202:203], v[124:125], v[200:201] op_sel_hi:[1,0]
	v_pk_mul_f32 v[226:227], v[126:127], v[200:201] op_sel_hi:[1,0]
	v_pk_mul_f32 v[252:253], v[120:121], v[200:201] op_sel_hi:[1,0]
	v_pk_mul_f32 v[200:201], v[122:123], v[200:201] op_sel_hi:[1,0]
	v_lshl_add_u64 v[230:231], v[204:205], 1, s[8:9]
	v_lshl_add_u64 v[224:225], v[222:223], 1, v[230:231]
	v_pk_mul_f32 v[228:229], v[154:155], v[226:227]
	v_pk_mul_f32 v[202:203], v[152:153], v[202:203]
	v_pk_mul_f32 v[226:227], v[158:159], v[200:201]
	v_pk_mul_f32 v[200:201], v[156:157], v[252:253]
	s_and_saveexec_b64 s[50:51], vcc
	s_xor_b64 s[50:51], exec, s[50:51]
	s_cbranch_execz .LBB0_779
	v_cvt_pk_bf16_f32 v202, v202, v203
	v_cvt_pk_bf16_f32 v203, v228, v229
	v_cvt_pk_bf16_f32 v204, v200, v201
	v_cvt_pk_bf16_f32 v205, v226, v227
	global_store_dwordx4 v[224:225], v[202:205], off
